# LN epilogues: H (bf16) tile stored first (sc1) and published as soon as it completes; fp32 X tile stored afterwards with plain stores (only re-read by the same workgroup)
# baseline (speedup 1.0000x reference)
.Lln1_pok1:
	v_add_f32_e32 v250, v250, v226
	v_add_f32_e32 v252, v252, v228
	v_add_f32_e32 v250, v250, v230
	v_add_f32_e32 v252, v252, v232
	v_add_f32_e32 v250, v250, v234
	v_add_f32_e32 v252, v252, v236
	v_add_f32_e32 v250, v250, v238
	v_add_f32_e32 v252, v252, v240
	v_add_f32_e32 v250, v250, v206
	v_add_f32_e32 v252, v252, v208
	v_add_f32_e32 v250, v250, v210
	v_add_f32_e32 v252, v252, v212
	v_add_f32_e32 v250, v250, v214
	v_add_f32_e32 v252, v252, v216
	v_add_f32_e32 v250, v250, v218
	v_add_f32_e32 v252, v252, v220
	global_load_dwordx4 v[226:229], v246, s[22:23]
	global_load_dwordx4 v[230:233], v246, s[22:23] offset:64
	global_load_dwordx4 v[234:237], v246, s[22:23] offset:128
	global_load_dwordx4 v[238:241], v246, s[22:23] offset:192
	v_mov_b32_e32 v206, v250
	v_mov_b32_e32 v207, v252
	v_mul_f32_e32 v208, 0x3a800000, v206
	v_mul_f32_e32 v209, v208, v208
	v_mov_b32_e32 v216, 0x3a800000
	v_fma_f32 v209, v207, v216, -v209
	v_max_f32_e32 v209, 0, v209
	v_add_f32_e32 v209, 0x3727c5ac, v209
	v_rsq_f32_e32 v209, v209
	v_mov_b32_e32 v210, v208
	v_mov_b32_e32 v211, v208
	v_mov_b32_e32 v214, v209
	v_mov_b32_e32 v215, v209
	s_nop 1
	v_permlane16_swap_b32_e32 v210, v211
	v_permlane16_swap_b32_e32 v214, v215
	v_mov_b32_e32 v212, v210
	v_mov_b32_e32 v213, v211
	v_mov_b32_e32 v216, v214
	v_mov_b32_e32 v217, v215
	s_nop 1
	v_permlane32_swap_b32_e32 v210, v212
	v_permlane32_swap_b32_e32 v211, v213
	v_permlane32_swap_b32_e32 v214, v216
	v_permlane32_swap_b32_e32 v215, v217
	v_readfirstlane_b32 s64, v137
	s_lshr_b32 s64, s64, 6
	s_lshl_b32 s64, s64, 14
	v_and_b32_e32 v222, 63, v137
	v_and_b32_e32 v246, 15, v222
	v_lshrrev_b32_e32 v247, 4, v222
	v_and_b32_e32 v248, 3, v246
	v_xor_b32_e32 v248, v248, v247
	v_lshlrev_b32_e32 v248, 4, v248
	v_lshl_add_u32 v248, v246, 8, v248
	v_add_u32_e32 v248, s64, v248
	v_lshl_add_u32 v249, v222, 4, s64
	v_add_u32_e32 v250, s36, v247
	v_lshlrev_b32_e32 v250, 12, v250
	v_xor_b32_e32 v251, v246, v247
	v_lshl_add_u32 v250, v251, 4, v250
	s_lshl_b32 s65, s37, 2
	v_add_u32_e32 v250, s65, v250
	v_sub_f32_e32 v62, v62, v210
	v_sub_f32_e32 v63, v63, v210
	v_sub_f32_e32 v64, v64, v210
	v_sub_f32_e32 v65, v65, v210
	v_mul_f32_e32 v62, v214, v62
	v_mul_f32_e32 v63, v214, v63
	v_mul_f32_e32 v64, v214, v64
	v_mul_f32_e32 v65, v214, v65
	v_fma_f32 v62, v66, v62, v90
	v_fma_f32 v63, v67, v63, v91
	v_fma_f32 v64, v68, v64, v92
	v_fma_f32 v65, v69, v65, v93
	v_sub_f32_e32 v86, v86, v210
	v_sub_f32_e32 v87, v87, v210
	v_sub_f32_e32 v88, v88, v210
	v_sub_f32_e32 v89, v89, v210
	v_mul_f32_e32 v86, v214, v86
	v_mul_f32_e32 v87, v214, v87
	v_mul_f32_e32 v88, v214, v88
	v_mul_f32_e32 v89, v214, v89
	v_fma_f32 v86, v74, v86, v94
	v_fma_f32 v87, v75, v87, v95
	v_fma_f32 v88, v76, v88, v96
	v_fma_f32 v89, v77, v89, v97
	v_sub_f32_e32 v70, v70, v210
	v_sub_f32_e32 v71, v71, v210
	v_sub_f32_e32 v72, v72, v210
	v_sub_f32_e32 v73, v73, v210
	v_mul_f32_e32 v70, v214, v70
	v_mul_f32_e32 v71, v214, v71
	v_mul_f32_e32 v72, v214, v72
	v_mul_f32_e32 v73, v214, v73
	v_fma_f32 v70, v78, v70, v108
	v_fma_f32 v71, v79, v71, v109
	v_fma_f32 v72, v80, v72, v110
	v_fma_f32 v73, v81, v73, v111
	v_sub_f32_e32 v176, v176, v210
	v_sub_f32_e32 v177, v177, v210
	v_sub_f32_e32 v178, v178, v210
	v_sub_f32_e32 v179, v179, v210
	v_mul_f32_e32 v176, v214, v176
	v_mul_f32_e32 v177, v214, v177
	v_mul_f32_e32 v178, v214, v178
	v_mul_f32_e32 v179, v214, v179
	v_fma_f32 v176, v82, v176, v172
	v_fma_f32 v177, v83, v177, v173
	v_fma_f32 v178, v84, v178, v174
	v_fma_f32 v179, v85, v179, v175
	v_sub_f32_e32 v202, v202, v211
	v_sub_f32_e32 v203, v203, v211
	v_sub_f32_e32 v204, v204, v211
	v_sub_f32_e32 v205, v205, v211
	v_mul_f32_e32 v202, v215, v202
	v_mul_f32_e32 v203, v215, v203
	v_mul_f32_e32 v204, v215, v204
	v_mul_f32_e32 v205, v215, v205
	v_fma_f32 v202, v66, v202, v90
	v_fma_f32 v203, v67, v203, v91
	v_fma_f32 v204, v68, v204, v92
	v_fma_f32 v205, v69, v205, v93
	v_sub_f32_e32 v54, v54, v211
	v_sub_f32_e32 v55, v55, v211
	v_sub_f32_e32 v56, v56, v211
	v_sub_f32_e32 v57, v57, v211
	v_mul_f32_e32 v54, v215, v54
	v_mul_f32_e32 v55, v215, v55
	v_mul_f32_e32 v56, v215, v56
	v_mul_f32_e32 v57, v215, v57
	v_fma_f32 v54, v74, v54, v94
	v_fma_f32 v55, v75, v55, v95
	v_fma_f32 v56, v76, v56, v96
	v_fma_f32 v57, v77, v57, v97
	v_sub_f32_e32 v58, v58, v211
	v_sub_f32_e32 v59, v59, v211
	v_sub_f32_e32 v60, v60, v211
	v_sub_f32_e32 v61, v61, v211
	v_mul_f32_e32 v58, v215, v58
	v_mul_f32_e32 v59, v215, v59
	v_mul_f32_e32 v60, v215, v60
	v_mul_f32_e32 v61, v215, v61
	v_fma_f32 v58, v78, v58, v108
	v_fma_f32 v59, v79, v59, v109
	v_fma_f32 v60, v80, v60, v110
	v_fma_f32 v61, v81, v61, v111
	v_sub_f32_e32 v34, v34, v211
	v_sub_f32_e32 v35, v35, v211
	v_sub_f32_e32 v36, v36, v211
	v_sub_f32_e32 v37, v37, v211
	v_mul_f32_e32 v34, v215, v34
	v_mul_f32_e32 v35, v215, v35
	v_mul_f32_e32 v36, v215, v36
	v_mul_f32_e32 v37, v215, v37
	v_fma_f32 v34, v82, v34, v172
	v_fma_f32 v35, v83, v35, v173
	v_fma_f32 v36, v84, v36, v174
	v_fma_f32 v37, v85, v37, v175
	v_sub_f32_e32 v30, v30, v212
	v_sub_f32_e32 v31, v31, v212
	v_sub_f32_e32 v32, v32, v212
	v_sub_f32_e32 v33, v33, v212
	v_mul_f32_e32 v30, v216, v30
	v_mul_f32_e32 v31, v216, v31
	v_mul_f32_e32 v32, v216, v32
	v_mul_f32_e32 v33, v216, v33
	v_fma_f32 v30, v66, v30, v90
	v_fma_f32 v31, v67, v31, v91
	v_fma_f32 v32, v68, v32, v92
	v_fma_f32 v33, v69, v33, v93
	v_sub_f32_e32 v26, v26, v212
	v_sub_f32_e32 v27, v27, v212
	v_sub_f32_e32 v28, v28, v212
	v_sub_f32_e32 v29, v29, v212
	v_mul_f32_e32 v26, v216, v26
	v_mul_f32_e32 v27, v216, v27
	v_mul_f32_e32 v28, v216, v28
	v_mul_f32_e32 v29, v216, v29
	v_fma_f32 v26, v74, v26, v94
	v_fma_f32 v27, v75, v27, v95
	v_fma_f32 v28, v76, v28, v96
	v_fma_f32 v29, v77, v29, v97
	v_sub_f32_e32 v22, v22, v212
	v_sub_f32_e32 v23, v23, v212
	v_sub_f32_e32 v24, v24, v212
	v_sub_f32_e32 v25, v25, v212
	v_mul_f32_e32 v22, v216, v22
	v_mul_f32_e32 v23, v216, v23
	v_mul_f32_e32 v24, v216, v24
	v_mul_f32_e32 v25, v216, v25
	v_fma_f32 v22, v78, v22, v108
	v_fma_f32 v23, v79, v23, v109
	v_fma_f32 v24, v80, v24, v110
	v_fma_f32 v25, v81, v25, v111
	v_sub_f32_e32 v18, v18, v212
	v_sub_f32_e32 v19, v19, v212
	v_sub_f32_e32 v20, v20, v212
	v_sub_f32_e32 v21, v21, v212
	v_mul_f32_e32 v18, v216, v18
	v_mul_f32_e32 v19, v216, v19
	v_mul_f32_e32 v20, v216, v20
	v_mul_f32_e32 v21, v216, v21
	v_fma_f32 v18, v82, v18, v172
	v_fma_f32 v19, v83, v19, v173
	v_fma_f32 v20, v84, v20, v174
	v_fma_f32 v21, v85, v21, v175
	v_sub_f32_e32 v14, v14, v213
	v_sub_f32_e32 v15, v15, v213
	v_sub_f32_e32 v16, v16, v213
	v_sub_f32_e32 v17, v17, v213
	v_mul_f32_e32 v14, v217, v14
	v_mul_f32_e32 v15, v217, v15
	v_mul_f32_e32 v16, v217, v16
	v_mul_f32_e32 v17, v217, v17
	v_fma_f32 v14, v66, v14, v90
	v_fma_f32 v15, v67, v15, v91
	v_fma_f32 v16, v68, v16, v92
	v_fma_f32 v17, v69, v17, v93
	v_sub_f32_e32 v10, v10, v213
	v_sub_f32_e32 v11, v11, v213
	v_sub_f32_e32 v12, v12, v213
	v_sub_f32_e32 v13, v13, v213
	v_mul_f32_e32 v10, v217, v10
	v_mul_f32_e32 v11, v217, v11
	v_mul_f32_e32 v12, v217, v12
	v_mul_f32_e32 v13, v217, v13
	v_fma_f32 v10, v74, v10, v94
	v_fma_f32 v11, v75, v11, v95
	v_fma_f32 v12, v76, v12, v96
	v_fma_f32 v13, v77, v13, v97
	v_sub_f32_e32 v6, v6, v213
	v_sub_f32_e32 v7, v7, v213
	v_sub_f32_e32 v8, v8, v213
	v_sub_f32_e32 v9, v9, v213
	v_mul_f32_e32 v6, v217, v6
	v_mul_f32_e32 v7, v217, v7
	v_mul_f32_e32 v8, v217, v8
	v_mul_f32_e32 v9, v217, v9
	v_fma_f32 v6, v78, v6, v108
	v_fma_f32 v7, v79, v7, v109
	v_fma_f32 v8, v80, v8, v110
	v_fma_f32 v9, v81, v9, v111
	v_sub_f32_e32 v2, v2, v213
	v_sub_f32_e32 v3, v3, v213
	v_sub_f32_e32 v4, v4, v213
	v_sub_f32_e32 v5, v5, v213
	v_mul_f32_e32 v2, v217, v2
	v_mul_f32_e32 v3, v217, v3
	v_mul_f32_e32 v4, v217, v4
	v_mul_f32_e32 v5, v217, v5
	v_fma_f32 v2, v82, v2, v172
	v_fma_f32 v3, v83, v3, v173
	v_fma_f32 v4, v84, v4, v174
	v_fma_f32 v5, v85, v5, v175
	s_add_u32 s44, s94, 0x7b48000
	s_addc_u32 s45, s95, 0
	s_waitcnt vmcnt(0)
	v_add_f32_e32 v226, 1.0, v226
	v_add_f32_e32 v227, 1.0, v227
	v_add_f32_e32 v228, 1.0, v228
	v_add_f32_e32 v229, 1.0, v229
	v_add_f32_e32 v230, 1.0, v230
	v_add_f32_e32 v231, 1.0, v231
	v_add_f32_e32 v232, 1.0, v232
	v_add_f32_e32 v233, 1.0, v233
	v_add_f32_e32 v234, 1.0, v234
	v_add_f32_e32 v235, 1.0, v235
	v_add_f32_e32 v236, 1.0, v236
	v_add_f32_e32 v237, 1.0, v237
	v_add_f32_e32 v238, 1.0, v238
	v_add_f32_e32 v239, 1.0, v239
	v_add_f32_e32 v240, 1.0, v240
	v_add_f32_e32 v241, 1.0, v241
	v_and_b32_e32 v251, 7, v246
	v_lshlrev_b32_e32 v251, 1, v251
	v_or_b32_e32 v218, 0, v247
	v_xor_b32_e32 v218, v218, v251
	v_lshlrev_b32_e32 v218, 3, v218
	v_lshl_add_u32 v218, v246, 7, v218
	v_add_u32_e32 v218, s64, v218
	v_or_b32_e32 v219, 4, v247
	v_xor_b32_e32 v219, v219, v251
	v_lshlrev_b32_e32 v219, 3, v219
	v_lshl_add_u32 v219, v246, 7, v219
	v_add_u32_e32 v219, s64, v219
	v_or_b32_e32 v220, 8, v247
	v_xor_b32_e32 v220, v220, v251
	v_lshlrev_b32_e32 v220, 3, v220
	v_lshl_add_u32 v220, v246, 7, v220
	v_add_u32_e32 v220, s64, v220
	v_or_b32_e32 v221, 12, v247
	v_xor_b32_e32 v221, v221, v251
	v_lshlrev_b32_e32 v221, 3, v221
	v_lshl_add_u32 v221, v246, 7, v221
	v_add_u32_e32 v221, s64, v221
	v_lshrrev_b32_e32 v247, 3, v222
	v_and_b32_e32 v251, 7, v222
	v_xor_b32_e32 v251, v251, v247
	v_add_u32_e32 v247, s36, v247
	v_lshlrev_b32_e32 v247, 11, v247
	v_lshl_add_u32 v247, v251, 4, v247
	s_lshl_b32 s65, s37, 1
	v_add_u32_e32 v247, s65, v247
	v_fma_f32 v66, v226, v62, v38
	v_fma_f32 v67, v227, v63, v39
	v_fma_f32 v68, v228, v64, v40
	v_fma_f32 v69, v229, v65, v41
	v_cvt_pk_bf16_f32 v66, v66, v67
	v_cvt_pk_bf16_f32 v67, v68, v69
	ds_write_b64 v218, v[66:67] offset:0
	v_fma_f32 v74, v230, v86, v42
	v_fma_f32 v75, v231, v87, v43
	v_fma_f32 v76, v232, v88, v44
	v_fma_f32 v77, v233, v89, v45
	v_cvt_pk_bf16_f32 v74, v74, v75
	v_cvt_pk_bf16_f32 v75, v76, v77
	ds_write_b64 v219, v[74:75] offset:0
	v_fma_f32 v66, v234, v70, v46
	v_fma_f32 v67, v235, v71, v47
	v_fma_f32 v68, v236, v72, v48
	v_fma_f32 v69, v237, v73, v49
	v_cvt_pk_bf16_f32 v66, v66, v67
	v_cvt_pk_bf16_f32 v67, v68, v69
	ds_write_b64 v220, v[66:67] offset:0
	v_fma_f32 v74, v238, v176, v50
	v_fma_f32 v75, v239, v177, v51
	v_fma_f32 v76, v240, v178, v52
	v_fma_f32 v77, v241, v179, v53
	v_cvt_pk_bf16_f32 v74, v74, v75
	v_cvt_pk_bf16_f32 v75, v76, v77
	ds_write_b64 v221, v[74:75] offset:0
	v_fma_f32 v66, v226, v202, v38
	v_fma_f32 v67, v227, v203, v39
	v_fma_f32 v68, v228, v204, v40
	v_fma_f32 v69, v229, v205, v41
	v_cvt_pk_bf16_f32 v66, v66, v67
	v_cvt_pk_bf16_f32 v67, v68, v69
	ds_write_b64 v218, v[66:67] offset:2048
	v_fma_f32 v74, v230, v54, v42
	v_fma_f32 v75, v231, v55, v43
	v_fma_f32 v76, v232, v56, v44
	v_fma_f32 v77, v233, v57, v45
	v_cvt_pk_bf16_f32 v74, v74, v75
	v_cvt_pk_bf16_f32 v75, v76, v77
	ds_write_b64 v219, v[74:75] offset:2048
	v_fma_f32 v66, v234, v58, v46
	v_fma_f32 v67, v235, v59, v47
	v_fma_f32 v68, v236, v60, v48
	v_fma_f32 v69, v237, v61, v49
	v_cvt_pk_bf16_f32 v66, v66, v67
	v_cvt_pk_bf16_f32 v67, v68, v69
	ds_write_b64 v220, v[66:67] offset:2048
	v_fma_f32 v74, v238, v34, v50
	v_fma_f32 v75, v239, v35, v51
	v_fma_f32 v76, v240, v36, v52
	v_fma_f32 v77, v241, v37, v53
	v_cvt_pk_bf16_f32 v74, v74, v75
	v_cvt_pk_bf16_f32 v75, v76, v77
	ds_write_b64 v221, v[74:75] offset:2048
	v_fma_f32 v66, v226, v30, v38
	v_fma_f32 v67, v227, v31, v39
	v_fma_f32 v68, v228, v32, v40
	v_fma_f32 v69, v229, v33, v41
	v_cvt_pk_bf16_f32 v66, v66, v67
	v_cvt_pk_bf16_f32 v67, v68, v69
	ds_write_b64 v218, v[66:67] offset:4096
	v_fma_f32 v74, v230, v26, v42
	v_fma_f32 v75, v231, v27, v43
	v_fma_f32 v76, v232, v28, v44
	v_fma_f32 v77, v233, v29, v45
	v_cvt_pk_bf16_f32 v74, v74, v75
	v_cvt_pk_bf16_f32 v75, v76, v77
	ds_write_b64 v219, v[74:75] offset:4096
	v_fma_f32 v66, v234, v22, v46
	v_fma_f32 v67, v235, v23, v47
	v_fma_f32 v68, v236, v24, v48
	v_fma_f32 v69, v237, v25, v49
	v_cvt_pk_bf16_f32 v66, v66, v67
	v_cvt_pk_bf16_f32 v67, v68, v69
	ds_write_b64 v220, v[66:67] offset:4096
	v_fma_f32 v74, v238, v18, v50
	v_fma_f32 v75, v239, v19, v51
	v_fma_f32 v76, v240, v20, v52
	v_fma_f32 v77, v241, v21, v53
	v_cvt_pk_bf16_f32 v74, v74, v75
	v_cvt_pk_bf16_f32 v75, v76, v77
	ds_write_b64 v221, v[74:75] offset:4096
	v_fma_f32 v66, v226, v14, v38
	v_fma_f32 v67, v227, v15, v39
	v_fma_f32 v68, v228, v16, v40
	v_fma_f32 v69, v229, v17, v41
	v_cvt_pk_bf16_f32 v66, v66, v67
	v_cvt_pk_bf16_f32 v67, v68, v69
	ds_write_b64 v218, v[66:67] offset:6144
	v_fma_f32 v74, v230, v10, v42
	v_fma_f32 v75, v231, v11, v43
	v_fma_f32 v76, v232, v12, v44
	v_fma_f32 v77, v233, v13, v45
	v_cvt_pk_bf16_f32 v74, v74, v75
	v_cvt_pk_bf16_f32 v75, v76, v77
	ds_write_b64 v219, v[74:75] offset:6144
	v_fma_f32 v66, v234, v6, v46
	v_fma_f32 v67, v235, v7, v47
	v_fma_f32 v68, v236, v8, v48
	v_fma_f32 v69, v237, v9, v49
	v_cvt_pk_bf16_f32 v66, v66, v67
	v_cvt_pk_bf16_f32 v67, v68, v69
	ds_write_b64 v220, v[66:67] offset:6144
	v_fma_f32 v74, v238, v2, v50
	v_fma_f32 v75, v239, v3, v51
	v_fma_f32 v76, v240, v4, v52
	v_fma_f32 v77, v241, v5, v53
	v_cvt_pk_bf16_f32 v74, v74, v75
	v_cvt_pk_bf16_f32 v75, v76, v77
	ds_write_b64 v221, v[74:75] offset:6144
	s_waitcnt lgkmcnt(0)
	ds_read_b128 v[66:69], v249 offset:0
	ds_read_b128 v[74:77], v249 offset:1024
	ds_read_b128 v[78:81], v249 offset:2048
	ds_read_b128 v[82:85], v249 offset:3072
	ds_read_b128 v[90:93], v249 offset:4096
	ds_read_b128 v[94:97], v249 offset:5120
	ds_read_b128 v[108:111], v249 offset:6144
	ds_read_b128 v[172:175], v249 offset:7168
	s_waitcnt lgkmcnt(7)
	global_store_dwordx4 v247, v[66:69], s[44:45] sc1
	s_waitcnt lgkmcnt(6)
	v_add_u32_e32 v251, 0x4000, v247
	global_store_dwordx4 v251, v[74:77], s[44:45] sc1
	s_waitcnt lgkmcnt(5)
	v_add_u32_e32 v251, 0x8000, v247
	global_store_dwordx4 v251, v[78:81], s[44:45] sc1
	s_waitcnt lgkmcnt(4)
	v_add_u32_e32 v251, 0xc000, v247
	global_store_dwordx4 v251, v[82:85], s[44:45] sc1
	s_waitcnt lgkmcnt(3)
	v_add_u32_e32 v251, 0x10000, v247
	global_store_dwordx4 v251, v[90:93], s[44:45] sc1
	s_waitcnt lgkmcnt(2)
	v_add_u32_e32 v251, 0x14000, v247
	global_store_dwordx4 v251, v[94:97], s[44:45] sc1
	s_waitcnt lgkmcnt(1)
	v_add_u32_e32 v251, 0x18000, v247
	global_store_dwordx4 v251, v[108:111], s[44:45] sc1
	s_waitcnt lgkmcnt(0)
	v_add_u32_e32 v251, 0x1c000, v247
	global_store_dwordx4 v251, v[172:175], s[44:45] sc1
	s_nop 1
	ds_write_b128 v248, v[62:65] offset:0
	ds_write_b128 v248, v[86:89] offset:64
	ds_write_b128 v248, v[70:73] offset:128
	ds_write_b128 v248, v[176:179] offset:192
	ds_write_b128 v248, v[202:205] offset:4096
	ds_write_b128 v248, v[54:57] offset:4160
	ds_write_b128 v248, v[58:61] offset:4224
	ds_write_b128 v248, v[34:37] offset:4288
	ds_write_b128 v248, v[30:33] offset:8192
	ds_write_b128 v248, v[26:29] offset:8256
	ds_write_b128 v248, v[22:25] offset:8320
	ds_write_b128 v248, v[18:21] offset:8384
	ds_write_b128 v248, v[14:17] offset:12288
	ds_write_b128 v248, v[10:13] offset:12352
	ds_write_b128 v248, v[6:9] offset:12416
	ds_write_b128 v248, v[2:5] offset:12480
	s_waitcnt lgkmcnt(0)
	ds_read_b128 v[66:69], v249 offset:0
	ds_read_b128 v[74:77], v249 offset:1024
	ds_read_b128 v[78:81], v249 offset:2048
	ds_read_b128 v[82:85], v249 offset:3072
	ds_read_b128 v[90:93], v249 offset:4096
	ds_read_b128 v[94:97], v249 offset:5120
	ds_read_b128 v[108:111], v249 offset:6144
	ds_read_b128 v[172:175], v249 offset:7168
	s_waitcnt lgkmcnt(7)
	global_store_dwordx4 v250, v[66:69], s[26:27]
	s_waitcnt lgkmcnt(6)
	v_add_u32_e32 v251, 0x4000, v250
	global_store_dwordx4 v251, v[74:77], s[26:27]
	s_waitcnt lgkmcnt(5)
	v_add_u32_e32 v251, 0x8000, v250
	global_store_dwordx4 v251, v[78:81], s[26:27]
	s_waitcnt lgkmcnt(4)
	v_add_u32_e32 v251, 0xc000, v250
	global_store_dwordx4 v251, v[82:85], s[26:27]
	s_waitcnt lgkmcnt(3)
	v_add_u32_e32 v251, 0x10000, v250
	global_store_dwordx4 v251, v[90:93], s[26:27]
	s_waitcnt lgkmcnt(2)
	v_add_u32_e32 v251, 0x14000, v250
	global_store_dwordx4 v251, v[94:97], s[26:27]
	s_waitcnt lgkmcnt(1)
	v_add_u32_e32 v251, 0x18000, v250
	global_store_dwordx4 v251, v[108:111], s[26:27]
	s_waitcnt lgkmcnt(0)
	v_add_u32_e32 v251, 0x1c000, v250
	global_store_dwordx4 v251, v[172:175], s[26:27]
	s_nop 1
	ds_read_b128 v[66:69], v249 offset:8192
	ds_read_b128 v[74:77], v249 offset:9216
	ds_read_b128 v[78:81], v249 offset:10240
	ds_read_b128 v[82:85], v249 offset:11264
	ds_read_b128 v[90:93], v249 offset:12288
	ds_read_b128 v[94:97], v249 offset:13312
	ds_read_b128 v[108:111], v249 offset:14336
	ds_read_b128 v[172:175], v249 offset:15360
	s_waitcnt lgkmcnt(7)
	v_add_u32_e32 v251, 0x20000, v250
	global_store_dwordx4 v251, v[66:69], s[26:27]
	s_waitcnt lgkmcnt(6)
	v_add_u32_e32 v251, 0x24000, v250
	global_store_dwordx4 v251, v[74:77], s[26:27]
	s_waitcnt lgkmcnt(5)
	v_add_u32_e32 v251, 0x28000, v250
	global_store_dwordx4 v251, v[78:81], s[26:27]
	s_waitcnt lgkmcnt(4)
	v_add_u32_e32 v251, 0x2c000, v250
	global_store_dwordx4 v251, v[82:85], s[26:27]
	s_waitcnt lgkmcnt(3)
	v_add_u32_e32 v251, 0x30000, v250
	global_store_dwordx4 v251, v[90:93], s[26:27]
	s_waitcnt lgkmcnt(2)
	v_add_u32_e32 v251, 0x34000, v250
	global_store_dwordx4 v251, v[94:97], s[26:27]
	s_waitcnt lgkmcnt(1)
	v_add_u32_e32 v251, 0x38000, v250
	global_store_dwordx4 v251, v[108:111], s[26:27]
	s_waitcnt lgkmcnt(0)
	v_add_u32_e32 v251, 0x3c000, v250
	global_store_dwordx4 v251, v[172:175], s[26:27]
	s_nop 1
	s_waitcnt vmcnt(16)
	s_barrier
	v_readfirstlane_b32 s6, v137
	s_cmp_lt_u32 s6, 64
	s_cbranch_scc0 .Lln1_nodone
	s_mul_hi_i32 s6, s60, 0x2aaaaaab
	s_lshr_b32 s13, s6, 31
	s_ashr_i32 s6, s6, 2
	s_add_i32 s6, s6, s13
	s_mul_i32 s13, s6, 24
	s_sub_i32 s13, s60, s13
	s_lshl_b32 s13, s13, 3
	s_add_i32 s13, s13, s6
	s_lshl_b32 s13, s13, 4
	v_readlane_b32 s14, v255, 40
	s_add_i32 s14, s14, 0x5d0e1000
	v_mov_b32_e32 v247, s13
	v_mov_b32_e32 v248, s14
	v_mov_b32_e32 v249, s14
	v_mov_b32_e32 v250, s14
	v_mov_b32_e32 v251, s14
	s_add_u32 s36, s94, 0xcbc8000
	s_addc_u32 s37, s95, 0
	s_mov_b64 exec, 1
	global_store_dwordx4 v247, v[248:251], s[36:37] sc1
	s_mov_b64 exec, -1

.Lln2_nomod:
	v_mov_b32_e32 v206, v250
	v_mov_b32_e32 v207, v252
	v_mul_f32_e32 v208, 0x3a800000, v206
	v_mul_f32_e32 v209, v208, v208
	v_mov_b32_e32 v216, 0x3a800000
	v_fma_f32 v209, v207, v216, -v209
	v_max_f32_e32 v209, 0, v209
	v_add_f32_e32 v209, 0x3727c5ac, v209
	v_rsq_f32_e32 v209, v209
	v_mov_b32_e32 v210, v208
	v_mov_b32_e32 v211, v208
	v_mov_b32_e32 v214, v209
	v_mov_b32_e32 v215, v209
	s_nop 1
	v_permlane16_swap_b32_e32 v210, v211
	v_permlane16_swap_b32_e32 v214, v215
	v_mov_b32_e32 v212, v210
	v_mov_b32_e32 v213, v211
	v_mov_b32_e32 v216, v214
	v_mov_b32_e32 v217, v215
	s_nop 1
	v_permlane32_swap_b32_e32 v210, v212
	v_permlane32_swap_b32_e32 v211, v213
	v_permlane32_swap_b32_e32 v214, v216
	v_permlane32_swap_b32_e32 v215, v217
	s_cmp_eq_u32 s53, 3
	s_cselect_b32 s26, s92, s26
	s_cselect_b32 s27, s93, s27
	v_readfirstlane_b32 s54, v137
	s_lshr_b32 s54, s54, 6
	s_lshl_b32 s54, s54, 14
	v_and_b32_e32 v222, 63, v137
	v_and_b32_e32 v246, 15, v222
	v_lshrrev_b32_e32 v247, 4, v222
	v_and_b32_e32 v248, 3, v246
	v_xor_b32_e32 v248, v248, v247
	v_lshlrev_b32_e32 v248, 4, v248
	v_lshl_add_u32 v248, v246, 8, v248
	v_add_u32_e32 v248, s54, v248
	v_lshl_add_u32 v249, v222, 4, s54
	v_add_u32_e32 v250, s50, v247
	v_lshlrev_b32_e32 v250, 12, v250
	v_xor_b32_e32 v251, v246, v247
	v_lshl_add_u32 v250, v251, 4, v250
	s_lshl_b32 s55, s51, 2
	v_add_u32_e32 v250, s55, v250
	v_sub_f32_e32 v62, v62, v210
	v_sub_f32_e32 v63, v63, v210
	v_sub_f32_e32 v64, v64, v210
	v_sub_f32_e32 v65, v65, v210
	v_mul_f32_e32 v62, v214, v62
	v_mul_f32_e32 v63, v214, v63
	v_mul_f32_e32 v64, v214, v64
	v_mul_f32_e32 v65, v214, v65
	v_fma_f32 v62, v66, v62, v90
	v_fma_f32 v63, v67, v63, v91
	v_fma_f32 v64, v68, v64, v92
	v_fma_f32 v65, v69, v65, v93
	v_sub_f32_e32 v86, v86, v210
	v_sub_f32_e32 v87, v87, v210
	v_sub_f32_e32 v88, v88, v210
	v_sub_f32_e32 v89, v89, v210
	v_mul_f32_e32 v86, v214, v86
	v_mul_f32_e32 v87, v214, v87
	v_mul_f32_e32 v88, v214, v88
	v_mul_f32_e32 v89, v214, v89
	v_fma_f32 v86, v74, v86, v94
	v_fma_f32 v87, v75, v87, v95
	v_fma_f32 v88, v76, v88, v96
	v_fma_f32 v89, v77, v89, v97
	v_sub_f32_e32 v70, v70, v210
	v_sub_f32_e32 v71, v71, v210
	v_sub_f32_e32 v72, v72, v210
	v_sub_f32_e32 v73, v73, v210
	v_mul_f32_e32 v70, v214, v70
	v_mul_f32_e32 v71, v214, v71
	v_mul_f32_e32 v72, v214, v72
	v_mul_f32_e32 v73, v214, v73
	v_fma_f32 v70, v78, v70, v108
	v_fma_f32 v71, v79, v71, v109
	v_fma_f32 v72, v80, v72, v110
	v_fma_f32 v73, v81, v73, v111
	v_sub_f32_e32 v176, v176, v210
	v_sub_f32_e32 v177, v177, v210
	v_sub_f32_e32 v178, v178, v210
	v_sub_f32_e32 v179, v179, v210
	v_mul_f32_e32 v176, v214, v176
	v_mul_f32_e32 v177, v214, v177
	v_mul_f32_e32 v178, v214, v178
	v_mul_f32_e32 v179, v214, v179
	v_fma_f32 v176, v82, v176, v172
	v_fma_f32 v177, v83, v177, v173
	v_fma_f32 v178, v84, v178, v174
	v_fma_f32 v179, v85, v179, v175
	v_sub_f32_e32 v202, v202, v211
	v_sub_f32_e32 v203, v203, v211
	v_sub_f32_e32 v204, v204, v211
	v_sub_f32_e32 v205, v205, v211
	v_mul_f32_e32 v202, v215, v202
	v_mul_f32_e32 v203, v215, v203
	v_mul_f32_e32 v204, v215, v204
	v_mul_f32_e32 v205, v215, v205
	v_fma_f32 v202, v66, v202, v90
	v_fma_f32 v203, v67, v203, v91
	v_fma_f32 v204, v68, v204, v92
	v_fma_f32 v205, v69, v205, v93
	v_sub_f32_e32 v54, v54, v211
	v_sub_f32_e32 v55, v55, v211
	v_sub_f32_e32 v56, v56, v211
	v_sub_f32_e32 v57, v57, v211
	v_mul_f32_e32 v54, v215, v54
	v_mul_f32_e32 v55, v215, v55
	v_mul_f32_e32 v56, v215, v56
	v_mul_f32_e32 v57, v215, v57
	v_fma_f32 v54, v74, v54, v94
	v_fma_f32 v55, v75, v55, v95
	v_fma_f32 v56, v76, v56, v96
	v_fma_f32 v57, v77, v57, v97
	v_sub_f32_e32 v58, v58, v211
	v_sub_f32_e32 v59, v59, v211
	v_sub_f32_e32 v60, v60, v211
	v_sub_f32_e32 v61, v61, v211
	v_mul_f32_e32 v58, v215, v58
	v_mul_f32_e32 v59, v215, v59
	v_mul_f32_e32 v60, v215, v60
	v_mul_f32_e32 v61, v215, v61
	v_fma_f32 v58, v78, v58, v108
	v_fma_f32 v59, v79, v59, v109
	v_fma_f32 v60, v80, v60, v110
	v_fma_f32 v61, v81, v61, v111
	v_sub_f32_e32 v34, v34, v211
	v_sub_f32_e32 v35, v35, v211
	v_sub_f32_e32 v36, v36, v211
	v_sub_f32_e32 v37, v37, v211
	v_mul_f32_e32 v34, v215, v34
	v_mul_f32_e32 v35, v215, v35
	v_mul_f32_e32 v36, v215, v36
	v_mul_f32_e32 v37, v215, v37
	v_fma_f32 v34, v82, v34, v172
	v_fma_f32 v35, v83, v35, v173
	v_fma_f32 v36, v84, v36, v174
	v_fma_f32 v37, v85, v37, v175
	v_sub_f32_e32 v30, v30, v212
	v_sub_f32_e32 v31, v31, v212
	v_sub_f32_e32 v32, v32, v212
	v_sub_f32_e32 v33, v33, v212
	v_mul_f32_e32 v30, v216, v30
	v_mul_f32_e32 v31, v216, v31
	v_mul_f32_e32 v32, v216, v32
	v_mul_f32_e32 v33, v216, v33
	v_fma_f32 v30, v66, v30, v90
	v_fma_f32 v31, v67, v31, v91
	v_fma_f32 v32, v68, v32, v92
	v_fma_f32 v33, v69, v33, v93
	v_sub_f32_e32 v26, v26, v212
	v_sub_f32_e32 v27, v27, v212
	v_sub_f32_e32 v28, v28, v212
	v_sub_f32_e32 v29, v29, v212
	v_mul_f32_e32 v26, v216, v26
	v_mul_f32_e32 v27, v216, v27
	v_mul_f32_e32 v28, v216, v28
	v_mul_f32_e32 v29, v216, v29
	v_fma_f32 v26, v74, v26, v94
	v_fma_f32 v27, v75, v27, v95
	v_fma_f32 v28, v76, v28, v96
	v_fma_f32 v29, v77, v29, v97
	v_sub_f32_e32 v22, v22, v212
	v_sub_f32_e32 v23, v23, v212
	v_sub_f32_e32 v24, v24, v212
	v_sub_f32_e32 v25, v25, v212
	v_mul_f32_e32 v22, v216, v22
	v_mul_f32_e32 v23, v216, v23
	v_mul_f32_e32 v24, v216, v24
	v_mul_f32_e32 v25, v216, v25
	v_fma_f32 v22, v78, v22, v108
	v_fma_f32 v23, v79, v23, v109
	v_fma_f32 v24, v80, v24, v110
	v_fma_f32 v25, v81, v25, v111
	v_sub_f32_e32 v18, v18, v212
	v_sub_f32_e32 v19, v19, v212
	v_sub_f32_e32 v20, v20, v212
	v_sub_f32_e32 v21, v21, v212
	v_mul_f32_e32 v18, v216, v18
	v_mul_f32_e32 v19, v216, v19
	v_mul_f32_e32 v20, v216, v20
	v_mul_f32_e32 v21, v216, v21
	v_fma_f32 v18, v82, v18, v172
	v_fma_f32 v19, v83, v19, v173
	v_fma_f32 v20, v84, v20, v174
	v_fma_f32 v21, v85, v21, v175
	v_sub_f32_e32 v14, v14, v213
	v_sub_f32_e32 v15, v15, v213
	v_sub_f32_e32 v16, v16, v213
	v_sub_f32_e32 v17, v17, v213
	v_mul_f32_e32 v14, v217, v14
	v_mul_f32_e32 v15, v217, v15
	v_mul_f32_e32 v16, v217, v16
	v_mul_f32_e32 v17, v217, v17
	v_fma_f32 v14, v66, v14, v90
	v_fma_f32 v15, v67, v15, v91
	v_fma_f32 v16, v68, v16, v92
	v_fma_f32 v17, v69, v17, v93
	v_sub_f32_e32 v10, v10, v213
	v_sub_f32_e32 v11, v11, v213
	v_sub_f32_e32 v12, v12, v213
	v_sub_f32_e32 v13, v13, v213
	v_mul_f32_e32 v10, v217, v10
	v_mul_f32_e32 v11, v217, v11
	v_mul_f32_e32 v12, v217, v12
	v_mul_f32_e32 v13, v217, v13
	v_fma_f32 v10, v74, v10, v94
	v_fma_f32 v11, v75, v11, v95
	v_fma_f32 v12, v76, v12, v96
	v_fma_f32 v13, v77, v13, v97
	v_sub_f32_e32 v6, v6, v213
	v_sub_f32_e32 v7, v7, v213
	v_sub_f32_e32 v8, v8, v213
	v_sub_f32_e32 v9, v9, v213
	v_mul_f32_e32 v6, v217, v6
	v_mul_f32_e32 v7, v217, v7
	v_mul_f32_e32 v8, v217, v8
	v_mul_f32_e32 v9, v217, v9
	v_fma_f32 v6, v78, v6, v108
	v_fma_f32 v7, v79, v7, v109
	v_fma_f32 v8, v80, v8, v110
	v_fma_f32 v9, v81, v9, v111
	v_sub_f32_e32 v2, v2, v213
	v_sub_f32_e32 v3, v3, v213
	v_sub_f32_e32 v4, v4, v213
	v_sub_f32_e32 v5, v5, v213
	v_mul_f32_e32 v2, v217, v2
	v_mul_f32_e32 v3, v217, v3
	v_mul_f32_e32 v4, v217, v4
	v_mul_f32_e32 v5, v217, v5
	v_fma_f32 v2, v82, v2, v172
	v_fma_f32 v3, v83, v3, v173
	v_fma_f32 v4, v84, v4, v174
	v_fma_f32 v5, v85, v5, v175
	s_cmp_eq_u32 s53, 3
	s_cbranch_scc1 .Lln2_xpass
	s_add_u32 s34, s94, 0x7b48000
	s_addc_u32 s35, s95, 0
	s_waitcnt vmcnt(0)
	v_add_f32_e32 v226, 1.0, v226
	v_add_f32_e32 v227, 1.0, v227
	v_add_f32_e32 v228, 1.0, v228
	v_add_f32_e32 v229, 1.0, v229
	v_add_f32_e32 v230, 1.0, v230
	v_add_f32_e32 v231, 1.0, v231
	v_add_f32_e32 v232, 1.0, v232
	v_add_f32_e32 v233, 1.0, v233
	v_add_f32_e32 v234, 1.0, v234
	v_add_f32_e32 v235, 1.0, v235
	v_add_f32_e32 v236, 1.0, v236
	v_add_f32_e32 v237, 1.0, v237
	v_add_f32_e32 v238, 1.0, v238
	v_add_f32_e32 v239, 1.0, v239
	v_add_f32_e32 v240, 1.0, v240
	v_add_f32_e32 v241, 1.0, v241
	v_and_b32_e32 v251, 7, v246
	v_lshlrev_b32_e32 v251, 1, v251
	v_or_b32_e32 v218, 0, v247
	v_xor_b32_e32 v218, v218, v251
	v_lshlrev_b32_e32 v218, 3, v218
	v_lshl_add_u32 v218, v246, 7, v218
	v_add_u32_e32 v218, s54, v218
	v_or_b32_e32 v219, 4, v247
	v_xor_b32_e32 v219, v219, v251
	v_lshlrev_b32_e32 v219, 3, v219
	v_lshl_add_u32 v219, v246, 7, v219
	v_add_u32_e32 v219, s54, v219
	v_or_b32_e32 v220, 8, v247
	v_xor_b32_e32 v220, v220, v251
	v_lshlrev_b32_e32 v220, 3, v220
	v_lshl_add_u32 v220, v246, 7, v220
	v_add_u32_e32 v220, s54, v220
	v_or_b32_e32 v221, 12, v247
	v_xor_b32_e32 v221, v221, v251
	v_lshlrev_b32_e32 v221, 3, v221
	v_lshl_add_u32 v221, v246, 7, v221
	v_add_u32_e32 v221, s54, v221
	v_lshrrev_b32_e32 v247, 3, v222
	v_and_b32_e32 v251, 7, v222
	v_xor_b32_e32 v251, v251, v247
	v_add_u32_e32 v247, s50, v247
	v_lshlrev_b32_e32 v247, 11, v247
	v_lshl_add_u32 v247, v251, 4, v247
	s_lshl_b32 s55, s51, 1
	v_add_u32_e32 v247, s55, v247
	v_fma_f32 v66, v226, v62, v38
	v_fma_f32 v67, v227, v63, v39
	v_fma_f32 v68, v228, v64, v40
	v_fma_f32 v69, v229, v65, v41
	v_cvt_pk_bf16_f32 v66, v66, v67
	v_cvt_pk_bf16_f32 v67, v68, v69
	ds_write_b64 v218, v[66:67] offset:0
	v_fma_f32 v74, v230, v86, v42
	v_fma_f32 v75, v231, v87, v43
	v_fma_f32 v76, v232, v88, v44
	v_fma_f32 v77, v233, v89, v45
	v_cvt_pk_bf16_f32 v74, v74, v75
	v_cvt_pk_bf16_f32 v75, v76, v77
	ds_write_b64 v219, v[74:75] offset:0
	v_fma_f32 v66, v234, v70, v46
	v_fma_f32 v67, v235, v71, v47
	v_fma_f32 v68, v236, v72, v48
	v_fma_f32 v69, v237, v73, v49
	v_cvt_pk_bf16_f32 v66, v66, v67
	v_cvt_pk_bf16_f32 v67, v68, v69
	ds_write_b64 v220, v[66:67] offset:0
	v_fma_f32 v74, v238, v176, v50
	v_fma_f32 v75, v239, v177, v51
	v_fma_f32 v76, v240, v178, v52
	v_fma_f32 v77, v241, v179, v53
	v_cvt_pk_bf16_f32 v74, v74, v75
	v_cvt_pk_bf16_f32 v75, v76, v77
	ds_write_b64 v221, v[74:75] offset:0
	v_fma_f32 v66, v226, v202, v38
	v_fma_f32 v67, v227, v203, v39
	v_fma_f32 v68, v228, v204, v40
	v_fma_f32 v69, v229, v205, v41
	v_cvt_pk_bf16_f32 v66, v66, v67
	v_cvt_pk_bf16_f32 v67, v68, v69
	ds_write_b64 v218, v[66:67] offset:2048
	v_fma_f32 v74, v230, v54, v42
	v_fma_f32 v75, v231, v55, v43
	v_fma_f32 v76, v232, v56, v44
	v_fma_f32 v77, v233, v57, v45
	v_cvt_pk_bf16_f32 v74, v74, v75
	v_cvt_pk_bf16_f32 v75, v76, v77
	ds_write_b64 v219, v[74:75] offset:2048
	v_fma_f32 v66, v234, v58, v46
	v_fma_f32 v67, v235, v59, v47
	v_fma_f32 v68, v236, v60, v48
	v_fma_f32 v69, v237, v61, v49
	v_cvt_pk_bf16_f32 v66, v66, v67
	v_cvt_pk_bf16_f32 v67, v68, v69
	ds_write_b64 v220, v[66:67] offset:2048
	v_fma_f32 v74, v238, v34, v50
	v_fma_f32 v75, v239, v35, v51
	v_fma_f32 v76, v240, v36, v52
	v_fma_f32 v77, v241, v37, v53
	v_cvt_pk_bf16_f32 v74, v74, v75
	v_cvt_pk_bf16_f32 v75, v76, v77
	ds_write_b64 v221, v[74:75] offset:2048
	v_fma_f32 v66, v226, v30, v38
	v_fma_f32 v67, v227, v31, v39
	v_fma_f32 v68, v228, v32, v40
	v_fma_f32 v69, v229, v33, v41
	v_cvt_pk_bf16_f32 v66, v66, v67
	v_cvt_pk_bf16_f32 v67, v68, v69
	ds_write_b64 v218, v[66:67] offset:4096
	v_fma_f32 v74, v230, v26, v42
	v_fma_f32 v75, v231, v27, v43
	v_fma_f32 v76, v232, v28, v44
	v_fma_f32 v77, v233, v29, v45
	v_cvt_pk_bf16_f32 v74, v74, v75
	v_cvt_pk_bf16_f32 v75, v76, v77
	ds_write_b64 v219, v[74:75] offset:4096
	v_fma_f32 v66, v234, v22, v46
	v_fma_f32 v67, v235, v23, v47
	v_fma_f32 v68, v236, v24, v48
	v_fma_f32 v69, v237, v25, v49
	v_cvt_pk_bf16_f32 v66, v66, v67
	v_cvt_pk_bf16_f32 v67, v68, v69
	ds_write_b64 v220, v[66:67] offset:4096
	v_fma_f32 v74, v238, v18, v50
	v_fma_f32 v75, v239, v19, v51
	v_fma_f32 v76, v240, v20, v52
	v_fma_f32 v77, v241, v21, v53
	v_cvt_pk_bf16_f32 v74, v74, v75
	v_cvt_pk_bf16_f32 v75, v76, v77
	ds_write_b64 v221, v[74:75] offset:4096
	v_fma_f32 v66, v226, v14, v38
	v_fma_f32 v67, v227, v15, v39
	v_fma_f32 v68, v228, v16, v40
	v_fma_f32 v69, v229, v17, v41
	v_cvt_pk_bf16_f32 v66, v66, v67
	v_cvt_pk_bf16_f32 v67, v68, v69
	ds_write_b64 v218, v[66:67] offset:6144
	v_fma_f32 v74, v230, v10, v42
	v_fma_f32 v75, v231, v11, v43
	v_fma_f32 v76, v232, v12, v44
	v_fma_f32 v77, v233, v13, v45
	v_cvt_pk_bf16_f32 v74, v74, v75
	v_cvt_pk_bf16_f32 v75, v76, v77
	ds_write_b64 v219, v[74:75] offset:6144
	v_fma_f32 v66, v234, v6, v46
	v_fma_f32 v67, v235, v7, v47
	v_fma_f32 v68, v236, v8, v48
	v_fma_f32 v69, v237, v9, v49
	v_cvt_pk_bf16_f32 v66, v66, v67
	v_cvt_pk_bf16_f32 v67, v68, v69
	ds_write_b64 v220, v[66:67] offset:6144
	v_fma_f32 v74, v238, v2, v50
	v_fma_f32 v75, v239, v3, v51
	v_fma_f32 v76, v240, v4, v52
	v_fma_f32 v77, v241, v5, v53
	v_cvt_pk_bf16_f32 v74, v74, v75
	v_cvt_pk_bf16_f32 v75, v76, v77
	ds_write_b64 v221, v[74:75] offset:6144
	s_waitcnt lgkmcnt(0)
	ds_read_b128 v[66:69], v249 offset:0
	ds_read_b128 v[74:77], v249 offset:1024
	ds_read_b128 v[78:81], v249 offset:2048
	ds_read_b128 v[82:85], v249 offset:3072
	ds_read_b128 v[90:93], v249 offset:4096
	ds_read_b128 v[94:97], v249 offset:5120
	ds_read_b128 v[108:111], v249 offset:6144
	ds_read_b128 v[172:175], v249 offset:7168
	s_waitcnt lgkmcnt(7)
	global_store_dwordx4 v247, v[66:69], s[34:35] sc1
	s_waitcnt lgkmcnt(6)
	v_add_u32_e32 v251, 0x4000, v247
	global_store_dwordx4 v251, v[74:77], s[34:35] sc1
	s_waitcnt lgkmcnt(5)
	v_add_u32_e32 v251, 0x8000, v247
	global_store_dwordx4 v251, v[78:81], s[34:35] sc1
	s_waitcnt lgkmcnt(4)
	v_add_u32_e32 v251, 0xc000, v247
	global_store_dwordx4 v251, v[82:85], s[34:35] sc1
	s_waitcnt lgkmcnt(3)
	v_add_u32_e32 v251, 0x10000, v247
	global_store_dwordx4 v251, v[90:93], s[34:35] sc1
	s_waitcnt lgkmcnt(2)
	v_add_u32_e32 v251, 0x14000, v247
	global_store_dwordx4 v251, v[94:97], s[34:35] sc1
	s_waitcnt lgkmcnt(1)
	v_add_u32_e32 v251, 0x18000, v247
	global_store_dwordx4 v251, v[108:111], s[34:35] sc1
	s_waitcnt lgkmcnt(0)
	v_add_u32_e32 v251, 0x1c000, v247
	global_store_dwordx4 v251, v[172:175], s[34:35] sc1
	s_nop 1
.Lln2_xpass:
	ds_write_b128 v248, v[62:65] offset:0
	ds_write_b128 v248, v[86:89] offset:64
	ds_write_b128 v248, v[70:73] offset:128
	ds_write_b128 v248, v[176:179] offset:192
	ds_write_b128 v248, v[202:205] offset:4096
	ds_write_b128 v248, v[54:57] offset:4160
	ds_write_b128 v248, v[58:61] offset:4224
	ds_write_b128 v248, v[34:37] offset:4288
	ds_write_b128 v248, v[30:33] offset:8192
	ds_write_b128 v248, v[26:29] offset:8256
	ds_write_b128 v248, v[22:25] offset:8320
	ds_write_b128 v248, v[18:21] offset:8384
	ds_write_b128 v248, v[14:17] offset:12288
	ds_write_b128 v248, v[10:13] offset:12352
	ds_write_b128 v248, v[6:9] offset:12416
	ds_write_b128 v248, v[2:5] offset:12480
	s_waitcnt lgkmcnt(0)
	ds_read_b128 v[66:69], v249 offset:0
	ds_read_b128 v[74:77], v249 offset:1024
	ds_read_b128 v[78:81], v249 offset:2048
	ds_read_b128 v[82:85], v249 offset:3072
	ds_read_b128 v[90:93], v249 offset:4096
	ds_read_b128 v[94:97], v249 offset:5120
	ds_read_b128 v[108:111], v249 offset:6144
	ds_read_b128 v[172:175], v249 offset:7168
	s_waitcnt lgkmcnt(7)
	global_store_dwordx4 v250, v[66:69], s[26:27]
	s_waitcnt lgkmcnt(6)
	v_add_u32_e32 v251, 0x4000, v250
	global_store_dwordx4 v251, v[74:77], s[26:27]
	s_waitcnt lgkmcnt(5)
	v_add_u32_e32 v251, 0x8000, v250
	global_store_dwordx4 v251, v[78:81], s[26:27]
	s_waitcnt lgkmcnt(4)
	v_add_u32_e32 v251, 0xc000, v250
	global_store_dwordx4 v251, v[82:85], s[26:27]
	s_waitcnt lgkmcnt(3)
	v_add_u32_e32 v251, 0x10000, v250
	global_store_dwordx4 v251, v[90:93], s[26:27]
	s_waitcnt lgkmcnt(2)
	v_add_u32_e32 v251, 0x14000, v250
	global_store_dwordx4 v251, v[94:97], s[26:27]
	s_waitcnt lgkmcnt(1)
	v_add_u32_e32 v251, 0x18000, v250
	global_store_dwordx4 v251, v[108:111], s[26:27]
	s_waitcnt lgkmcnt(0)
	v_add_u32_e32 v251, 0x1c000, v250
	global_store_dwordx4 v251, v[172:175], s[26:27]
	s_nop 1
	ds_read_b128 v[66:69], v249 offset:8192
	ds_read_b128 v[74:77], v249 offset:9216
	ds_read_b128 v[78:81], v249 offset:10240
	ds_read_b128 v[82:85], v249 offset:11264
	ds_read_b128 v[90:93], v249 offset:12288
	ds_read_b128 v[94:97], v249 offset:13312
	ds_read_b128 v[108:111], v249 offset:14336
	ds_read_b128 v[172:175], v249 offset:15360
	s_waitcnt lgkmcnt(7)
	v_add_u32_e32 v251, 0x20000, v250
	global_store_dwordx4 v251, v[66:69], s[26:27]
	s_waitcnt lgkmcnt(6)
	v_add_u32_e32 v251, 0x24000, v250
	global_store_dwordx4 v251, v[74:77], s[26:27]
	s_waitcnt lgkmcnt(5)
	v_add_u32_e32 v251, 0x28000, v250
	global_store_dwordx4 v251, v[78:81], s[26:27]
	s_waitcnt lgkmcnt(4)
	v_add_u32_e32 v251, 0x2c000, v250
	global_store_dwordx4 v251, v[82:85], s[26:27]
	s_waitcnt lgkmcnt(3)
	v_add_u32_e32 v251, 0x30000, v250
	global_store_dwordx4 v251, v[90:93], s[26:27]
	s_waitcnt lgkmcnt(2)
	v_add_u32_e32 v251, 0x34000, v250
	global_store_dwordx4 v251, v[94:97], s[26:27]
	s_waitcnt lgkmcnt(1)
	v_add_u32_e32 v251, 0x38000, v250
	global_store_dwordx4 v251, v[108:111], s[26:27]
	s_waitcnt lgkmcnt(0)
	v_add_u32_e32 v251, 0x3c000, v250
	global_store_dwordx4 v251, v[172:175], s[26:27]
	s_nop 1
.Lln2_end:
	s_waitcnt vmcnt(16)
	s_barrier
	v_readfirstlane_b32 s13, v137
	s_cmp_lt_u32 s13, 64
	s_cbranch_scc0 .Lln2_nodone
	s_mul_hi_i32 s19, s70, 0x2aaaaaab
	s_lshr_b32 s13, s19, 31
	s_ashr_i32 s19, s19, 2
	s_add_i32 s19, s19, s13
	s_mul_i32 s13, s19, 24
	s_sub_i32 s13, s70, s13
	s_lshl_b32 s13, s13, 3
	s_add_i32 s13, s13, s19
	s_lshl_b32 s13, s13, 4
	v_readlane_b32 s14, v255, 40
	s_add_i32 s14, s14, 0x5d0e3000
	v_mov_b32_e32 v247, s13
	v_mov_b32_e32 v248, s14
	v_mov_b32_e32 v249, s14
	v_mov_b32_e32 v250, s14
	v_mov_b32_e32 v251, s14
	s_add_u32 s36, s94, 0xcbcc000
	s_addc_u32 s37, s95, 0
	s_mov_b64 exec, 1
	global_store_dwordx4 v247, v[248:251], s[36:37] sc1
	s_mov_b64 exec, -1
